# attention epilogues: half-rows exchanged with v_permlane32_swap pairs so the O tile is stored with 8 dwordx4 per unit instead of 16 dwordx2
# speedup vs baseline: 1.0222x; 1.0160x over previous
; DI u32x2 pk4(f32x4 v) { u32x2 r; r.x = pk2(v[0], v[1]); r.y = pk2(v[2], v[3]); return r; }
; template <bool ISB>
; DI void attn_unit(int u, int hq, int qoff, int nq, const bf16_t* Qb, const bf16_t* Kb, const bf16_t* Vtb, bf16_t* O, const float* sinks, const LAS float* biasL, LAS unsigned char* ring, int lane) {
;     ...
;     for (int qb = 0; qb < 2; ++qb) {
;         if (qb >= nq) continue;
;         const float l = lrun[qb] + __shfl_xor(lrun[qb], 32), inv = 1.f / l;
;         bf16_t* op = O + (size_t)(64 * u + qoff + 32 * qb + r) * DM + (ISB ? 512 : 0) + hq * 64 + 4 * hh;
; #pragma unroll
;         for (int db = 0; db < 2; ++db)
; #pragma unroll
;             for (int i4 = 0; i4 < 4; ++i4) { f32x4 v = {o[qb][db][4 * i4] * inv, o[qb][db][4 * i4 + 1] * inv, o[qb][db][4 * i4 + 2] * inv, o[qb][db][4 * i4 + 3] * inv};
;                 *(u32x2*)(op + 32 * db + 8 * i4) = pk4(v); }
;     }
.LBB0_641:
	v_cmp_lt_i32_e32 vcc, v156, v157
	s_nop 1
	v_cndmask_b32_e32 v64, v176, v156, vcc
	v_lshlrev_b32_e32 v67, 2, v64
	ds_bpermute_b32 v65, v67, v181
	v_or_b32_e32 v64, s6, v182
	s_waitcnt vmcnt(0) lgkmcnt(0)
	v_add_f32_e32 v66, v181, v65
	v_div_scale_f32 v68, s[0:1], v66, v66, 1.0
	v_rcp_f32_e32 v69, v68
	v_div_scale_f32 v70, vcc, 1.0, v66, 1.0
	v_ashrrev_i32_e32 v65, 31, v64
	v_fma_f32 v71, -v68, v69, 1.0
	v_fmac_f32_e32 v69, v71, v69
	v_mul_f32_e32 v71, v70, v69
	v_fma_f32 v72, -v68, v71, v70
	v_fmac_f32_e32 v71, v72, v69
	v_fma_f32 v68, -v68, v71, v70
	v_div_fmas_f32 v68, v68, v69, v71
	v_div_fixup_f32 v66, v68, v66, 1.0
	ds_bpermute_b32 v77, v67, v179
	v_and_b32_e32 v76, 32, v176
	v_lshrrev_b32_e32 v76, 2, v76
	v_lshlrev_b64 v[68:69], 11, v[64:65]
	v_lshl_add_u64 v[68:69], v[174:175], 0, v[68:69]
	v_add_co_u32_e32 v68, vcc, v76, v68
	s_nop 1
	v_addc_co_u32_e32 v69, vcc, 0, v69, vcc
	v_add_u32_e32 v84, 32, v64
	v_ashrrev_i32_e32 v85, 31, v84
	v_lshlrev_b64 v[84:85], 11, v[84:85]
	v_lshl_add_u64 v[84:85], v[174:175], 0, v[84:85]
	v_add_co_u32_e32 v84, vcc, v76, v84
	s_nop 1
	v_addc_co_u32_e32 v85, vcc, 0, v85, vcc
	s_waitcnt lgkmcnt(0)
	v_add_f32_e32 v77, v179, v77
	v_div_scale_f32 v88, s[0:1], v77, v77, 1.0
	v_rcp_f32_e32 v89, v88
	v_div_scale_f32 v90, vcc, 1.0, v77, 1.0
	v_fma_f32 v91, -v88, v89, 1.0
	v_fmac_f32_e32 v89, v91, v89
	v_mul_f32_e32 v91, v90, v89
	v_fma_f32 v92, -v88, v91, v90
	v_fmac_f32_e32 v91, v92, v89
	v_fma_f32 v88, -v88, v91, v90
	v_div_fmas_f32 v88, v88, v89, v91
	v_div_fixup_f32 v78, v88, v77, 1.0
	v_pk_mul_f32 v[32:33], v[32:33], v[66:67] op_sel_hi:[1,0]
	v_pk_mul_f32 v[34:35], v[34:35], v[66:67] op_sel_hi:[1,0]
	v_pk_mul_f32 v[36:37], v[36:37], v[66:67] op_sel_hi:[1,0]
	v_pk_mul_f32 v[38:39], v[38:39], v[66:67] op_sel_hi:[1,0]
	v_pk_mul_f32 v[40:41], v[40:41], v[66:67] op_sel_hi:[1,0]
	v_pk_mul_f32 v[42:43], v[42:43], v[66:67] op_sel_hi:[1,0]
	v_pk_mul_f32 v[44:45], v[44:45], v[66:67] op_sel_hi:[1,0]
	v_pk_mul_f32 v[46:47], v[46:47], v[66:67] op_sel_hi:[1,0]
	v_cvt_pk_bf16_f32 v32, v32, v33
	v_cvt_pk_bf16_f32 v33, v34, v35
	v_cvt_pk_bf16_f32 v34, v36, v37
	v_cvt_pk_bf16_f32 v35, v38, v39
	v_cvt_pk_bf16_f32 v40, v40, v41
	v_cvt_pk_bf16_f32 v41, v42, v43
	v_cvt_pk_bf16_f32 v42, v44, v45
	v_cvt_pk_bf16_f32 v43, v46, v47
	s_nop 1
	v_permlane32_swap_b32_e32 v32, v34
	v_permlane32_swap_b32_e32 v33, v35
	v_permlane32_swap_b32_e32 v40, v42
	v_permlane32_swap_b32_e32 v41, v43
	global_store_dwordx4 v[68:69], v[32:35], off offset:1024
	global_store_dwordx4 v[68:69], v[40:43], off offset:1056
	v_pk_mul_f32 v[0:1], v[0:1], v[66:67] op_sel_hi:[1,0]
	v_pk_mul_f32 v[2:3], v[2:3], v[66:67] op_sel_hi:[1,0]
	v_pk_mul_f32 v[4:5], v[4:5], v[66:67] op_sel_hi:[1,0]
	v_pk_mul_f32 v[6:7], v[6:7], v[66:67] op_sel_hi:[1,0]
	v_pk_mul_f32 v[8:9], v[8:9], v[66:67] op_sel_hi:[1,0]
	v_pk_mul_f32 v[10:11], v[10:11], v[66:67] op_sel_hi:[1,0]
	v_pk_mul_f32 v[12:13], v[12:13], v[66:67] op_sel_hi:[1,0]
	v_pk_mul_f32 v[14:15], v[14:15], v[66:67] op_sel_hi:[1,0]
	v_cvt_pk_bf16_f32 v0, v0, v1
	v_cvt_pk_bf16_f32 v1, v2, v3
	v_cvt_pk_bf16_f32 v2, v4, v5
	v_cvt_pk_bf16_f32 v3, v6, v7
	v_cvt_pk_bf16_f32 v8, v8, v9
	v_cvt_pk_bf16_f32 v9, v10, v11
	v_cvt_pk_bf16_f32 v10, v12, v13
	v_cvt_pk_bf16_f32 v11, v14, v15
	s_nop 1
	v_permlane32_swap_b32_e32 v0, v2
	v_permlane32_swap_b32_e32 v1, v3
	v_permlane32_swap_b32_e32 v8, v10
	v_permlane32_swap_b32_e32 v9, v11
	global_store_dwordx4 v[68:69], v[0:3], off offset:1088
	global_store_dwordx4 v[68:69], v[8:11], off offset:1120
	v_pk_mul_f32 v[48:49], v[48:49], v[78:79] op_sel_hi:[1,0]
	v_pk_mul_f32 v[50:51], v[50:51], v[78:79] op_sel_hi:[1,0]
	v_pk_mul_f32 v[52:53], v[52:53], v[78:79] op_sel_hi:[1,0]
	v_pk_mul_f32 v[54:55], v[54:55], v[78:79] op_sel_hi:[1,0]
	v_pk_mul_f32 v[56:57], v[56:57], v[78:79] op_sel_hi:[1,0]
	v_pk_mul_f32 v[58:59], v[58:59], v[78:79] op_sel_hi:[1,0]
	v_pk_mul_f32 v[60:61], v[60:61], v[78:79] op_sel_hi:[1,0]
	v_pk_mul_f32 v[62:63], v[62:63], v[78:79] op_sel_hi:[1,0]
	v_cvt_pk_bf16_f32 v48, v48, v49
	v_cvt_pk_bf16_f32 v49, v50, v51
	v_cvt_pk_bf16_f32 v50, v52, v53
	v_cvt_pk_bf16_f32 v51, v54, v55
	v_cvt_pk_bf16_f32 v56, v56, v57
	v_cvt_pk_bf16_f32 v57, v58, v59
	v_cvt_pk_bf16_f32 v58, v60, v61
	v_cvt_pk_bf16_f32 v59, v62, v63
	s_nop 1
	v_permlane32_swap_b32_e32 v48, v50
	v_permlane32_swap_b32_e32 v49, v51
	v_permlane32_swap_b32_e32 v56, v58
	v_permlane32_swap_b32_e32 v57, v59
	global_store_dwordx4 v[84:85], v[48:51], off offset:1024
	global_store_dwordx4 v[84:85], v[56:59], off offset:1056
	v_pk_mul_f32 v[16:17], v[16:17], v[78:79] op_sel_hi:[1,0]
	v_pk_mul_f32 v[18:19], v[18:19], v[78:79] op_sel_hi:[1,0]
	v_pk_mul_f32 v[20:21], v[20:21], v[78:79] op_sel_hi:[1,0]
	v_pk_mul_f32 v[22:23], v[22:23], v[78:79] op_sel_hi:[1,0]
	v_pk_mul_f32 v[24:25], v[24:25], v[78:79] op_sel_hi:[1,0]
	v_pk_mul_f32 v[26:27], v[26:27], v[78:79] op_sel_hi:[1,0]
	v_pk_mul_f32 v[28:29], v[28:29], v[78:79] op_sel_hi:[1,0]
	v_pk_mul_f32 v[30:31], v[30:31], v[78:79] op_sel_hi:[1,0]
	v_cvt_pk_bf16_f32 v16, v16, v17
	v_cvt_pk_bf16_f32 v17, v18, v19
	v_cvt_pk_bf16_f32 v18, v20, v21
	v_cvt_pk_bf16_f32 v19, v22, v23
	v_cvt_pk_bf16_f32 v24, v24, v25
	v_cvt_pk_bf16_f32 v25, v26, v27
	v_cvt_pk_bf16_f32 v26, v28, v29
	v_cvt_pk_bf16_f32 v27, v30, v31
	s_nop 1
	v_permlane32_swap_b32_e32 v16, v18
	v_permlane32_swap_b32_e32 v17, v19
	v_permlane32_swap_b32_e32 v24, v26
	v_permlane32_swap_b32_e32 v25, v27
	global_store_dwordx4 v[84:85], v[16:19], off offset:1088
	global_store_dwordx4 v[84:85], v[24:27], off offset:1120
	s_mov_b64 s[0:1], 0

; DI u32x2 pk4(f32x4 v) { u32x2 r; r.x = pk2(v[0], v[1]); r.y = pk2(v[2], v[3]); return r; }
; template <bool ISB>
; DI void attn_unit(int u, int hq, int qoff, int nq, const bf16_t* Qb, const bf16_t* Kb, const bf16_t* Vtb, bf16_t* O, const float* sinks, const LAS float* biasL, LAS unsigned char* ring, int lane) {
;     ...
;     for (int qb = 0; qb < 2; ++qb) {
;         if (qb >= nq) continue;
;         const float l = lrun[qb] + __shfl_xor(lrun[qb], 32), inv = 1.f / l;
;         bf16_t* op = O + (size_t)(64 * u + qoff + 32 * qb + r) * DM + (ISB ? 512 : 0) + hq * 64 + 4 * hh;
; #pragma unroll
;         for (int db = 0; db < 2; ++db)
; #pragma unroll
;             for (int i4 = 0; i4 < 4; ++i4) { f32x4 v = {o[qb][db][4 * i4] * inv, o[qb][db][4 * i4 + 1] * inv, o[qb][db][4 * i4 + 2] * inv, o[qb][db][4 * i4 + 3] * inv};
;                 *(u32x2*)(op + 32 * db + 8 * i4) = pk4(v); }
;     }
.LBB0_696:
	v_cmp_lt_i32_e32 vcc, v192, v193
	s_nop 1
	v_cndmask_b32_e32 v66, v191, v192, vcc
	v_lshlrev_b32_e32 v68, 2, v66
	ds_bpermute_b32 v67, v68, v65
	v_or_b32_e32 v66, s91, v188
	s_waitcnt lgkmcnt(0)
	v_add_f32_e32 v65, v65, v67
	v_div_scale_f32 v69, s[0:1], v65, v65, 1.0
	v_rcp_f32_e32 v70, v69
	v_div_scale_f32 v71, vcc, 1.0, v65, 1.0
	v_ashrrev_i32_e32 v67, 31, v66
	v_fma_f32 v72, -v69, v70, 1.0
	v_fmac_f32_e32 v70, v72, v70
	v_mul_f32_e32 v72, v71, v70
	v_fma_f32 v73, -v69, v72, v71
	v_fmac_f32_e32 v72, v73, v70
	v_fma_f32 v69, -v69, v72, v71
	v_div_fmas_f32 v69, v69, v70, v72
	v_div_fixup_f32 v70, v69, v65, 1.0
	v_and_b32_e32 v100, 32, v191
	v_lshrrev_b32_e32 v100, 2, v100
	v_lshlrev_b64 v[72:73], 11, v[66:67]
	v_lshl_add_u64 v[72:73], v[174:175], 0, v[72:73]
	v_add_co_u32_e32 v72, vcc, v100, v72
	s_nop 1
	v_addc_co_u32_e32 v73, vcc, 0, v73, vcc
	v_pk_mul_f32 v[16:17], v[16:17], v[70:71] op_sel_hi:[1,0]
	v_pk_mul_f32 v[18:19], v[18:19], v[70:71] op_sel_hi:[1,0]
	v_pk_mul_f32 v[20:21], v[20:21], v[70:71] op_sel_hi:[1,0]
	v_pk_mul_f32 v[22:23], v[22:23], v[70:71] op_sel_hi:[1,0]
	v_pk_mul_f32 v[24:25], v[24:25], v[70:71] op_sel_hi:[1,0]
	v_pk_mul_f32 v[26:27], v[26:27], v[70:71] op_sel_hi:[1,0]
	v_pk_mul_f32 v[28:29], v[28:29], v[70:71] op_sel_hi:[1,0]
	v_pk_mul_f32 v[30:31], v[30:31], v[70:71] op_sel_hi:[1,0]
	v_cvt_pk_bf16_f32 v16, v16, v17
	v_cvt_pk_bf16_f32 v17, v18, v19
	v_cvt_pk_bf16_f32 v18, v20, v21
	v_cvt_pk_bf16_f32 v19, v22, v23
	v_cvt_pk_bf16_f32 v24, v24, v25
	v_cvt_pk_bf16_f32 v25, v26, v27
	v_cvt_pk_bf16_f32 v26, v28, v29
	v_cvt_pk_bf16_f32 v27, v30, v31
	s_nop 1
	v_permlane32_swap_b32_e32 v16, v18
	v_permlane32_swap_b32_e32 v17, v19
	v_permlane32_swap_b32_e32 v24, v26
	v_permlane32_swap_b32_e32 v25, v27
	global_store_dwordx4 v[72:73], v[16:19], off
	global_store_dwordx4 v[72:73], v[24:27], off offset:32
	v_pk_mul_f32 v[0:1], v[0:1], v[70:71] op_sel_hi:[1,0]
	v_pk_mul_f32 v[2:3], v[2:3], v[70:71] op_sel_hi:[1,0]
	v_pk_mul_f32 v[4:5], v[4:5], v[70:71] op_sel_hi:[1,0]
	v_pk_mul_f32 v[6:7], v[6:7], v[70:71] op_sel_hi:[1,0]
	v_pk_mul_f32 v[8:9], v[8:9], v[70:71] op_sel_hi:[1,0]
	v_pk_mul_f32 v[10:11], v[10:11], v[70:71] op_sel_hi:[1,0]
	v_pk_mul_f32 v[12:13], v[12:13], v[70:71] op_sel_hi:[1,0]
	v_pk_mul_f32 v[14:15], v[14:15], v[70:71] op_sel_hi:[1,0]
	v_cvt_pk_bf16_f32 v0, v0, v1
	v_cvt_pk_bf16_f32 v1, v2, v3
	v_cvt_pk_bf16_f32 v2, v4, v5
	v_cvt_pk_bf16_f32 v3, v6, v7
	v_cvt_pk_bf16_f32 v8, v8, v9
	v_cvt_pk_bf16_f32 v9, v10, v11
	v_cvt_pk_bf16_f32 v10, v12, v13
	v_cvt_pk_bf16_f32 v11, v14, v15
	s_nop 1
	v_permlane32_swap_b32_e32 v0, v2
	v_permlane32_swap_b32_e32 v1, v3
	v_permlane32_swap_b32_e32 v8, v10
	v_permlane32_swap_b32_e32 v9, v11
	global_store_dwordx4 v[72:73], v[0:3], off offset:64
	global_store_dwordx4 v[72:73], v[8:11], off offset:96
	s_and_b64 vcc, exec, s[26:27]
	s_cbranch_vccz .LBB0_698
	ds_bpermute_b32 v101, v68, v64
	v_add_u32_e32 v102, 32, v66
	v_ashrrev_i32_e32 v103, 31, v102
	v_lshlrev_b64 v[102:103], 11, v[102:103]
	v_lshl_add_u64 v[102:103], v[174:175], 0, v[102:103]
	v_add_co_u32_e32 v102, vcc, v100, v102
	s_nop 1
	v_addc_co_u32_e32 v103, vcc, 0, v103, vcc
	s_waitcnt lgkmcnt(0)
	v_add_f32_e32 v101, v64, v101
	v_div_scale_f32 v106, s[0:1], v101, v101, 1.0
	v_rcp_f32_e32 v107, v106
	v_div_scale_f32 v108, vcc, 1.0, v101, 1.0
	v_fma_f32 v109, -v106, v107, 1.0
	v_fmac_f32_e32 v107, v109, v107
	v_mul_f32_e32 v109, v108, v107
	v_fma_f32 v110, -v106, v109, v108
	v_fmac_f32_e32 v109, v110, v107
	v_fma_f32 v106, -v106, v109, v108
	v_div_fmas_f32 v106, v106, v107, v109
	v_div_fixup_f32 v104, v106, v101, 1.0
	v_pk_mul_f32 v[48:49], v[48:49], v[104:105] op_sel_hi:[1,0]
	v_pk_mul_f32 v[50:51], v[50:51], v[104:105] op_sel_hi:[1,0]
	v_pk_mul_f32 v[52:53], v[52:53], v[104:105] op_sel_hi:[1,0]
	v_pk_mul_f32 v[54:55], v[54:55], v[104:105] op_sel_hi:[1,0]
	v_pk_mul_f32 v[56:57], v[56:57], v[104:105] op_sel_hi:[1,0]
	v_pk_mul_f32 v[58:59], v[58:59], v[104:105] op_sel_hi:[1,0]
	v_pk_mul_f32 v[60:61], v[60:61], v[104:105] op_sel_hi:[1,0]
	v_pk_mul_f32 v[62:63], v[62:63], v[104:105] op_sel_hi:[1,0]
	v_cvt_pk_bf16_f32 v48, v48, v49
	v_cvt_pk_bf16_f32 v49, v50, v51
	v_cvt_pk_bf16_f32 v50, v52, v53
	v_cvt_pk_bf16_f32 v51, v54, v55
	v_cvt_pk_bf16_f32 v56, v56, v57
	v_cvt_pk_bf16_f32 v57, v58, v59
	v_cvt_pk_bf16_f32 v58, v60, v61
	v_cvt_pk_bf16_f32 v59, v62, v63
	s_nop 1
	v_permlane32_swap_b32_e32 v48, v50
	v_permlane32_swap_b32_e32 v49, v51
	v_permlane32_swap_b32_e32 v56, v58
	v_permlane32_swap_b32_e32 v57, v59
	global_store_dwordx4 v[102:103], v[48:51], off
	global_store_dwordx4 v[102:103], v[56:59], off offset:32
	v_pk_mul_f32 v[32:33], v[32:33], v[104:105] op_sel_hi:[1,0]
	v_pk_mul_f32 v[34:35], v[34:35], v[104:105] op_sel_hi:[1,0]
	v_pk_mul_f32 v[36:37], v[36:37], v[104:105] op_sel_hi:[1,0]
	v_pk_mul_f32 v[38:39], v[38:39], v[104:105] op_sel_hi:[1,0]
	v_pk_mul_f32 v[40:41], v[40:41], v[104:105] op_sel_hi:[1,0]
	v_pk_mul_f32 v[42:43], v[42:43], v[104:105] op_sel_hi:[1,0]
	v_pk_mul_f32 v[44:45], v[44:45], v[104:105] op_sel_hi:[1,0]
	v_pk_mul_f32 v[46:47], v[46:47], v[104:105] op_sel_hi:[1,0]
	v_cvt_pk_bf16_f32 v32, v32, v33
	v_cvt_pk_bf16_f32 v33, v34, v35
	v_cvt_pk_bf16_f32 v34, v36, v37
	v_cvt_pk_bf16_f32 v35, v38, v39
	v_cvt_pk_bf16_f32 v40, v40, v41
	v_cvt_pk_bf16_f32 v41, v42, v43
	v_cvt_pk_bf16_f32 v42, v44, v45
	v_cvt_pk_bf16_f32 v43, v46, v47
	s_nop 1
	v_permlane32_swap_b32_e32 v32, v34
	v_permlane32_swap_b32_e32 v33, v35
	v_permlane32_swap_b32_e32 v40, v42
	v_permlane32_swap_b32_e32 v41, v43
	global_store_dwordx4 v[102:103], v[32:35], off offset:64
	global_store_dwordx4 v[102:103], v[40:43], off offset:96
	s_mov_b64 s[0:1], 0
	s_branch .LBB0_699
